# GLA o-accumulation: the 8 S^T operand fragments prefetched right after the chunk's second barrier into VGPRs idle in the mixer phase (was read-wait-mfma); on top of v59
# speedup vs baseline: 1.0017x; 1.0017x over previous
; #define MFMA16(a, b, c) __builtin_amdgcn_mfma_f32_16x16x32_bf16((a), (b), (c), 0, 0, 0)
; __device__ __forceinline__ void gla_unit(const Params& p, const WS& ws, int u, bool dry = false) {
;     ...
; #pragma unroll
;     for (int mt = 0; mt < 4; ++mt) {
;       u32x2 pk = (u32x2){0u, 0u};
;       if (mt <= w) {
;         f32x4 a = (f32x4){0.f, 0.f, 0.f, 0.f};
; #pragma unroll
;         for (int ks = 0; ks < 4; ++ks) {
;           const bf16x8 kf = *(const bf16x8*)(KIs + (16 * mt + lr) * 136 + 32 * ks + 8 * lq);
;           a = MFMA16(kf, xq[ks], a);
;         }
;         const int ip = 16 * mt + 4 * lq;
;         const float v0 = (ip + 0 <= irow) ? a[0] : 0.f, v1 = (ip + 1 <= irow) ? a[1] : 0.f;
;         const float v2 = (ip + 2 <= irow) ? a[2] : 0.f, v3 = (ip + 3 <= irow) ? a[3] : 0.f;
;         pk.x = cvt_pk_bf16(v0, v1); pk.y = cvt_pk_bf16(v2, v3);
;       }
;       *(u32x2*)(Ps + irow * 72 + 16 * mt + 4 * lq) = pk;
;     }
;     __syncthreads();
;     f32x4 oacc[2];
;     oacc[0] = (f32x4){0.f, 0.f, 0.f, 0.f}; oacc[1] = (f32x4){0.f, 0.f, 0.f, 0.f};
; #pragma unroll
;     for (int ks = 0; ks < 2; ++ks) {
;       if (2 * ks <= w) {
;         const bf16x8 pb = *(const bf16x8*)(Ps + irow * 72 + 32 * ks + 8 * lq);
; #pragma unroll
;         for (int mt = 0; mt < 2; ++mt) {
;           const bf16x8 vf = *(const bf16x8*)(VTs + (16 * mt + lr) * 72 + (((4 * ks + lq) ^ (((16 * mt + lr) >> 3) & 3)) << 3));
;           oacc[mt] = MFMA16(vf, pb, oacc[mt]);
;         }
;       }
.LBB0_1630:
	s_or_b64 exec, exec, s[12:13]
	v_mov_b32_e32 v112, 0
	v_mov_b32_e32 v113, 0
	v_mov_b32_e32 v114, 0
	v_mov_b32_e32 v115, 0
	v_mov_b32_e32 v108, 0
	v_mov_b32_e32 v109, 0
	v_mov_b32_e32 v110, 0
	v_mov_b32_e32 v111, 0
	v_mov_b32_e32 v116, 0
	v_mov_b32_e32 v117, 0
	v_mov_b32_e32 v118, 0
	v_mov_b32_e32 v119, 0
	v_mov_b32_e32 v120, 0
	v_mov_b32_e32 v121, 0
	v_mov_b32_e32 v122, 0
	v_mov_b32_e32 v123, 0
	ds_write_b64 v182, v[14:15] offset:96
	s_waitcnt lgkmcnt(0)
	s_barrier
	ds_read_b128 v[212:215], v129 offset:57856
	ds_read_b128 v[216:219], v129 offset:62208
	ds_read_b128 v[220:223], v129 offset:57920
	ds_read_b128 v[224:227], v129 offset:62272
	ds_read_b128 v[228:231], v129 offset:57984
	ds_read_b128 v[232:235], v129 offset:62336
	ds_read_b128 v[244:247], v129 offset:58048
	ds_read_b128 v[248:251], v129 offset:62400
	s_and_saveexec_b64 s[12:13], vcc
	s_cbranch_execz .LBB0_1632
	ds_read_b128 v[108:111], v170 offset:53248
	ds_read_b128 v[116:119], v177
	ds_read_b128 v[120:123], v171 offset:53248
	s_waitcnt lgkmcnt(1)
	v_mfma_f32_16x16x32_bf16 v[112:115], v[108:111], v[116:119], 0
	s_waitcnt lgkmcnt(0)
	v_mfma_f32_16x16x32_bf16 v[108:111], v[120:123], v[116:119], 0
	s_nop 5
	v_mov_b32_e32 v116, v112
	v_mov_b32_e32 v117, v113
	v_mov_b32_e32 v118, v114
	v_mov_b32_e32 v119, v115
	v_mov_b32_e32 v120, v108
	v_mov_b32_e32 v121, v109
	v_mov_b32_e32 v122, v110
	v_mov_b32_e32 v123, v111

; __device__ __forceinline__ bf16_t f2bf(float f) { return (bf16_t)(cvt_pk_bf16(f, 0.f) & 0xffffu); }
; #define MFMA16(a, b, c) __builtin_amdgcn_mfma_f32_16x16x32_bf16((a), (b), (c), 0, 0, 0)
; __device__ __forceinline__ void gla_unit(const Params& p, const WS& ws, int u, bool dry = false) {
;     ...
; #pragma unroll
;     for (int ks = 0; ks < 4; ++ks)
; #pragma unroll
;       for (int mt = 0; mt < 2; ++mt) {
;         const bf16x8 sf = *(const bf16x8*)(STs + (16 * mt + lr) * 136 + 32 * ks + 8 * lq);
;         oacc[mt] = MFMA16(sf, xq[ks], oacc[mt]);
;       }
;     {
;       const int t = 64 * c - 48 + irow;
;       float sq = 0.f;
; #pragma unroll
;       for (int mt = 0; mt < 2; ++mt) sq += oacc[mt][0] * oacc[mt][0] + oacc[mt][1] * oacc[mt][1] + oacc[mt][2] * oacc[mt][2] + oacc[mt][3] * oacc[mt][3];
;       sq += __shfl_xor(sq, 16); sq += __shfl_xor(sq, 32);
;       tpend = t;
;       sqpend = sq;
; #pragma unroll
;       for (int mt = 0; mt < 2; ++mt) { opend[mt].x = cvt_pk_bf16(oacc[mt][0], oacc[mt][1]); opend[mt].y = cvt_pk_bf16(oacc[mt][2], oacc[mt][3]); }
;     }
;     __syncthreads();
; #pragma unroll
;     for (int ntl = 0; ntl < 2; ++ntl) {
; #pragma unroll
;       for (int ks = 0; ks < 2; ++ks) {
;         const bf16x8 kf = *(const bf16x8*)(KIT + (16 * (2 * w + ntl) + lr) * 72 + (((4 * ks + lq) ^ (((16 * (2 * w + ntl) + lr) >> 3) & 7)) << 3));
; #pragma unroll
;         for (int mt = 0; mt < 2; ++mt) {
;           const bf16x8 vf = *(const bf16x8*)(VTs + (16 * mt + lr) * 72 + (((4 * ks + lq) ^ (((16 * mt + lr) >> 3) & 3)) << 3));
;           sacc[mt][ntl] = MFMA16(vf, kf, sacc[mt][ntl]);
;         }
;       }
;       const float e = ntl ? eb1 : eb0;
; #pragma unroll
;       for (int mt = 0; mt < 2; ++mt) {
;         sacc[mt][ntl] = scale4(sacc[mt][ntl], e);
; #pragma unroll
;         for (int jj = 0; jj < 4; ++jj) STs[(16 * mt + 4 * lq + jj) * 136 + 16 * (2 * w + ntl) + lr] = f2bf(sacc[mt][ntl][jj]);
;       }
;     }
.LBB0_1634:
	s_or_b64 exec, exec, s[12:13]
	s_nop 1
	s_nop 0
	s_nop 0
	s_cmp_gt_u32 s35, 32
	s_waitcnt lgkmcnt(0)
	v_mfma_f32_16x16x32_bf16 v[108:111], v[212:215], v[104:107], v[116:119]
	s_waitcnt lgkmcnt(0)
	v_mfma_f32_16x16x32_bf16 v[104:107], v[216:219], v[104:107], v[120:123]
	s_nop 0
	s_waitcnt lgkmcnt(0)
	v_mfma_f32_16x16x32_bf16 v[108:111], v[220:223], v[100:103], v[108:111]
	s_nop 0
	s_waitcnt lgkmcnt(0)
	v_mfma_f32_16x16x32_bf16 v[100:103], v[224:227], v[100:103], v[104:107]
	s_nop 2
	s_nop 0
	s_waitcnt lgkmcnt(0)
	v_mfma_f32_16x16x32_bf16 v[104:107], v[228:231], v[8:11], v[108:111]
	s_nop 2
	s_nop 0
	s_waitcnt lgkmcnt(0)
	v_mfma_f32_16x16x32_bf16 v[8:11], v[232:235], v[8:11], v[100:103]
	s_nop 2
	s_nop 0
	s_waitcnt lgkmcnt(0)
	v_mfma_f32_16x16x32_bf16 v[100:103], v[244:247], v[4:7], v[104:107]
	s_nop 2
	s_nop 0
	s_waitcnt lgkmcnt(0)
	s_barrier
	v_mfma_f32_16x16x32_bf16 v[6:9], v[248:251], v[4:7], v[8:11]
	s_nop 2
	v_mov_b32_e32 v10, v101
	v_mov_b32_e32 v4, v100
	s_nop 2
	v_mov_b32_e32 v11, v7
	v_mov_b32_e32 v5, v6
	v_pk_mul_f32 v[10:11], v[10:11], v[10:11]
	v_cvt_pk_bf16_f32 v6, v6, v7
	v_pk_fma_f32 v[4:5], v[4:5], v[4:5], v[10:11]
	v_mov_b32_e32 v10, v102
	v_mov_b32_e32 v11, v8
	v_pk_fma_f32 v[4:5], v[10:11], v[10:11], v[4:5]
	v_mov_b32_e32 v10, v103
	v_mov_b32_e32 v11, v9
	v_pk_fma_f32 v[4:5], v[10:11], v[10:11], v[4:5]
	v_cvt_pk_bf16_f32 v7, v8, v9
	v_add_f32_e32 v4, v4, v5
	ds_bpermute_b32 v5, v163, v4
	v_mov_b32_e32 v8, v208
	s_waitcnt lgkmcnt(0)
	v_add_f32_e32 v4, v4, v5
	ds_bpermute_b32 v5, v168, v4
	s_waitcnt lgkmcnt(0)
	v_add_f32_e32 v10, v4, v5
	v_cvt_pk_bf16_f32 v4, v100, v101
	v_cvt_pk_bf16_f32 v5, v102, v103
	ds_read_b128 v[100:103], v169 offset:34816
	ds_read_b128 v[104:107], v170 offset:53248
	s_waitcnt lgkmcnt(0)
	v_mfma_f32_16x16x32_bf16 v[84:87], v[104:107], v[100:103], v[84:87]
	ds_read_b128 v[104:107], v171 offset:53248
	s_waitcnt lgkmcnt(0)
	v_mfma_f32_16x16x32_bf16 v[96:99], v[104:107], v[100:103], v[96:99]
	ds_read_b128 v[100:103], v172 offset:34816
	ds_read_b128 v[104:107], v173 offset:53248
	s_waitcnt lgkmcnt(0)
	v_mfma_f32_16x16x32_bf16 v[84:87], v[104:107], v[100:103], v[84:87]
	ds_read_b128 v[104:107], v174 offset:53248
	s_waitcnt lgkmcnt(0)
	v_mfma_f32_16x16x32_bf16 v[96:99], v[104:107], v[100:103], v[96:99]
	s_nop 4
	v_mul_f32_e32 v84, v84, v8
	v_mul_f32_e32 v85, v85, v8
	v_mul_f32_e32 v86, v86, v8
	v_mul_f32_e32 v87, v87, v8
	s_nop 0
	v_cvt_pk_bf16_f32 v8, v84, s0
	ds_write_b16 v178, v8 offset:57856
	v_cvt_pk_bf16_f32 v8, v85, s0
	ds_write_b16 v178, v8 offset:58128
	v_cvt_pk_bf16_f32 v8, v86, s0
	ds_write_b16 v178, v8 offset:58400
	v_cvt_pk_bf16_f32 v8, v87, s0
	ds_write_b16 v178, v8 offset:58672
	s_nop 0
	v_mul_f32_e32 v96, v96, v208
	v_mul_f32_e32 v97, v97, v208
	v_mul_f32_e32 v98, v98, v208
	v_mul_f32_e32 v99, v99, v208
	s_nop 0
	v_cvt_pk_bf16_f32 v8, v96, s0
	ds_write_b16 v178, v8 offset:62208
	v_cvt_pk_bf16_f32 v8, v97, s0
	ds_write_b16 v178, v8 offset:62480
	v_cvt_pk_bf16_f32 v8, v98, s0
	ds_write_b16 v178, v8 offset:62752
	v_cvt_pk_bf16_f32 v8, v99, s0
	ds_write_b16 v178, v8 offset:63024
	ds_read_b128 v[100:103], v180 offset:34816
	ds_read_b128 v[104:107], v170 offset:53248
	s_waitcnt lgkmcnt(0)
	v_mfma_f32_16x16x32_bf16 v[88:91], v[104:107], v[100:103], v[88:91]
	ds_read_b128 v[104:107], v171 offset:53248
	v_mov_b32_e32 v8, v207
	s_waitcnt lgkmcnt(0)
	v_mfma_f32_16x16x32_bf16 v[92:95], v[104:107], v[100:103], v[92:95]
	ds_read_b128 v[100:103], v181 offset:34816
	ds_read_b128 v[104:107], v173 offset:53248
	s_waitcnt lgkmcnt(0)
	v_mfma_f32_16x16x32_bf16 v[88:91], v[104:107], v[100:103], v[88:91]
	ds_read_b128 v[104:107], v174 offset:53248
	s_waitcnt lgkmcnt(0)
	v_mfma_f32_16x16x32_bf16 v[92:95], v[104:107], v[100:103], v[92:95]
	s_nop 4
	v_mul_f32_e32 v88, v88, v8
	v_mul_f32_e32 v89, v89, v8
	v_mul_f32_e32 v90, v90, v8
	v_mul_f32_e32 v91, v91, v8
	s_nop 0
	v_cvt_pk_bf16_f32 v8, v88, s0
	ds_write_b16 v178, v8 offset:57888
	v_cvt_pk_bf16_f32 v8, v89, s0
	ds_write_b16 v178, v8 offset:58160
	v_cvt_pk_bf16_f32 v8, v90, s0
	ds_write_b16 v178, v8 offset:58432
	v_cvt_pk_bf16_f32 v8, v91, s0
	ds_write_b16 v178, v8 offset:58704
	s_nop 0
	v_mul_f32_e32 v92, v92, v207
	v_mul_f32_e32 v93, v93, v207
	v_mul_f32_e32 v94, v94, v207
	v_mul_f32_e32 v95, v95, v207
	s_nop 0
	v_cvt_pk_bf16_f32 v8, v92, s0
	ds_write_b16 v178, v8 offset:62240
	v_cvt_pk_bf16_f32 v8, v93, s0
	ds_write_b16 v178, v8 offset:62512
	v_cvt_pk_bf16_f32 v8, v94, s0
	ds_write_b16 v178, v8 offset:62784
	v_cvt_pk_bf16_f32 v8, v95, s0
	ds_write_b16 v178, v8 offset:63056
	s_waitcnt lgkmcnt(0)
	s_barrier
; __device__ __forceinline__ void gla_unit(const Params& p, const WS& ws, int u, bool dry = false) {
;     ...
;   auto flush_o = [&]() {
;     if (tpend >= 0 && !dry) {
;       const size_t row = (size_t)(b * T_ + tpend);
; #pragma unroll
;       for (int mt = 0; mt < 2; ++mt) *(u32x2*)(ws.V + row * 1024 + hd * 256 + sl * 32 + 16 * mt + 4 * lq) = opend[mt];
;       if (lq == 0) ws.SSQ[row * 32 + hd * 8 + sl] = sqpend;
;     }
;   };
;   auto body = [&](int c, u32x4 (&qr)[4], u32x4 (&kr)[4], u32x4& vr, float (&ebl)[2]) {
; #pragma unroll
;     for (int i = 0; i < 4; ++i) {
;       const int ci = tid + 256 * i; const int row = ci >> 4, ch = ci & 15;
;       *(u32x4*)(QDs + row * 136 + ch * 8) = qr[i];
;       *(u32x4*)(KIs + row * 136 + ch * 8) = kr[i];
;       const unsigned kk[4] = {kr[i].x, kr[i].y, kr[i].z, kr[i].w};
; #pragma unroll
;       for (int e = 0; e < 4; ++e) {
;         KIT[(ch * 8 + 2 * e) * 72 + (row ^ ((ch & 7) << 3))] = (bf16_t)(kk[e] & 0xffffu);
;         KIT[(ch * 8 + 2 * e + 1) * 72 + (row ^ ((ch & 7) << 3))] = (bf16_t)(kk[e] >> 16);
;       }
;     }
;     {
;       const int row = tid >> 2, ch = tid & 3;
;       const unsigned vv[4] = {vr.x, vr.y, vr.z, vr.w};
; #pragma unroll
;       for (int e = 0; e < 4; ++e) {
;         VTs[(ch * 8 + 2 * e) * 72 + (row ^ (ch << 3))] = (bf16_t)(vv[e] & 0xffffu);
;         VTs[(ch * 8 + 2 * e + 1) * 72 + (row ^ (ch << 3))] = (bf16_t)(vv[e] >> 16);
;       }
;     }
;     const float eb0 = ebl[0], eb1 = ebl[1];
;     __syncthreads();
;     flush_o();
	s_cbranch_scc1 .LBB0_1663
	v_add_u32_e32 v207, s92, v161
	v_subrev_u32_e32 v8, 48, v207
	v_cmp_lt_i32_e64 s[80:81], -1, v8
	ds_write_b128 v147, v[44:47]
	ds_write_b128 v147, v[48:51] offset:17408
	ds_write_b16 v148, v48 offset:34816
	ds_write_b16_d16_hi v149, v48 offset:34960
	ds_write_b16 v148, v49 offset:35104
	ds_write_b16_d16_hi v148, v49 offset:35248
	ds_write_b16 v148, v50 offset:35392
	ds_write_b16_d16_hi v148, v50 offset:35536
	ds_write_b16 v148, v51 offset:35680
	ds_write_b16_d16_hi v148, v51 offset:35824
	ds_write_b128 v150, v[56:59]
	ds_write_b128 v150, v[52:55] offset:17408
	ds_write_b16 v151, v52 offset:34816
	ds_write_b16_d16_hi v152, v52 offset:34960
	ds_write_b16 v151, v53 offset:35104
	ds_write_b16_d16_hi v151, v53 offset:35248
	ds_write_b16 v151, v54 offset:35392
	ds_write_b16_d16_hi v151, v54 offset:35536
	ds_write_b16 v151, v55 offset:35680
	ds_write_b16_d16_hi v151, v55 offset:35824
	ds_write_b128 v153, v[64:67]
	ds_write_b128 v153, v[68:71] offset:17408
	ds_write_b16 v154, v68 offset:34816
	ds_write_b16_d16_hi v155, v68 offset:34960
	ds_write_b16 v154, v69 offset:35104
	ds_write_b16_d16_hi v154, v69 offset:35248
	ds_write_b16 v154, v70 offset:35392
	ds_write_b16_d16_hi v154, v70 offset:35536
	ds_write_b16 v154, v71 offset:35680
	ds_write_b16_d16_hi v154, v71 offset:35824
	ds_write_b128 v156, v[72:75]
	ds_write_b128 v156, v[76:79] offset:17408
	ds_write_b16 v157, v76 offset:34816
	ds_write_b16_d16_hi v158, v76 offset:34960
	ds_write_b16 v157, v77 offset:35104
	ds_write_b16_d16_hi v157, v77 offset:35248
	ds_write_b16 v157, v78 offset:35392
	ds_write_b16_d16_hi v157, v78 offset:35536
	ds_write_b16 v157, v79 offset:35680
	ds_write_b16_d16_hi v157, v79 offset:35824
	ds_write_b16 v159, v80 offset:53248
	ds_write_b16_d16_hi v160, v80 offset:53392
	ds_write_b16 v159, v81 offset:53536
	ds_write_b16_d16_hi v159, v81 offset:53680
	ds_write_b16 v159, v82 offset:53824
	ds_write_b16_d16_hi v159, v82 offset:53968
	ds_write_b16 v159, v83 offset:54112
	ds_write_b16_d16_hi v159, v83 offset:54256
	s_waitcnt lgkmcnt(0)
	s_barrier
	s_and_saveexec_b64 s[12:13], s[80:81]
	s_cbranch_execz .LBB0_1638
	v_add_u32_e32 v8, s92, v203
	v_ashrrev_i32_e32 v9, 31, v8
	v_lshlrev_b64 v[14:15], 11, v[8:9]
	v_lshl_add_u64 v[14:15], v[138:139], 0, v[14:15]
	global_store_dwordx2 v[14:15], v[4:5], off
	global_store_dwordx2 v[14:15], v[6:7], off offset:32
	s_and_b64 exec, exec, s[44:45]
	s_cbranch_execz .LBB0_1638
	v_lshlrev_b64 v[4:5], 7, v[8:9]
	v_lshl_add_u64 v[4:5], s[6:7], 0, v[4:5]
	global_store_dword v[4:5], v10, off

; __device__ __forceinline__ bf16_t f2bf(float f) { return (bf16_t)(cvt_pk_bf16(f, 0.f) & 0xffffu); }
; #define MFMA16(a, b, c) __builtin_amdgcn_mfma_f32_16x16x32_bf16((a), (b), (c), 0, 0, 0)
; __device__ __forceinline__ void gla_unit(const Params& p, const WS& ws, int u, bool dry = false) {
;     ...
; #pragma unroll
;     for (int ks = 0; ks < 4; ++ks)
; #pragma unroll
;       for (int mt = 0; mt < 2; ++mt) {
;         const bf16x8 sf = *(const bf16x8*)(STs + (16 * mt + lr) * 136 + 32 * ks + 8 * lq);
;         oacc[mt] = MFMA16(sf, xq[ks], oacc[mt]);
;       }
;     {
;       const int t = 64 * c - 48 + irow;
;       float sq = 0.f;
; #pragma unroll
;       for (int mt = 0; mt < 2; ++mt) sq += oacc[mt][0] * oacc[mt][0] + oacc[mt][1] * oacc[mt][1] + oacc[mt][2] * oacc[mt][2] + oacc[mt][3] * oacc[mt][3];
;       sq += __shfl_xor(sq, 16); sq += __shfl_xor(sq, 32);
;       tpend = t;
;       sqpend = sq;
; #pragma unroll
;       for (int mt = 0; mt < 2; ++mt) { opend[mt].x = cvt_pk_bf16(oacc[mt][0], oacc[mt][1]); opend[mt].y = cvt_pk_bf16(oacc[mt][2], oacc[mt][3]); }
;     }
;     __syncthreads();
; #pragma unroll
;     for (int ntl = 0; ntl < 2; ++ntl) {
; #pragma unroll
;       for (int ks = 0; ks < 2; ++ks) {
;         const bf16x8 kf = *(const bf16x8*)(KIT + (16 * (2 * w + ntl) + lr) * 72 + (((4 * ks + lq) ^ (((16 * (2 * w + ntl) + lr) >> 3) & 7)) << 3));
; #pragma unroll
;         for (int mt = 0; mt < 2; ++mt) {
;           const bf16x8 vf = *(const bf16x8*)(VTs + (16 * mt + lr) * 72 + (((4 * ks + lq) ^ (((16 * mt + lr) >> 3) & 3)) << 3));
;           sacc[mt][ntl] = MFMA16(vf, kf, sacc[mt][ntl]);
;         }
;       }
;       const float e = ntl ? eb1 : eb0;
; #pragma unroll
;       for (int mt = 0; mt < 2; ++mt) {
;         sacc[mt][ntl] = scale4(sacc[mt][ntl], e);
; #pragma unroll
;         for (int jj = 0; jj < 4; ++jj) STs[(16 * mt + 4 * lq + jj) * 136 + 16 * (2 * w + ntl) + lr] = f2bf(sacc[mt][ntl][jj]);
;       }
;     }
;     __syncthreads();
.LBB0_1662:
	s_or_b64 exec, exec, s[12:13]
	s_nop 1
	s_nop 0
	s_nop 0
	s_waitcnt lgkmcnt(0)
	v_mfma_f32_16x16x32_bf16 v[108:111], v[212:215], v[104:107], v[116:119]
	s_waitcnt lgkmcnt(0)
	v_mfma_f32_16x16x32_bf16 v[104:107], v[216:219], v[104:107], v[120:123]
	s_nop 0
	s_waitcnt lgkmcnt(0)
	v_mfma_f32_16x16x32_bf16 v[108:111], v[220:223], v[100:103], v[108:111]
	s_nop 0
	s_waitcnt lgkmcnt(0)
	v_mfma_f32_16x16x32_bf16 v[100:103], v[224:227], v[100:103], v[104:107]
	s_nop 2
	s_nop 0
	s_waitcnt lgkmcnt(0)
	v_mfma_f32_16x16x32_bf16 v[104:107], v[228:231], v[8:11], v[108:111]
	s_nop 2
	s_nop 0
	s_waitcnt lgkmcnt(0)
	v_mfma_f32_16x16x32_bf16 v[8:11], v[232:235], v[8:11], v[100:103]
	s_nop 2
	s_nop 0
	s_waitcnt lgkmcnt(0)
	v_mfma_f32_16x16x32_bf16 v[100:103], v[244:247], v[4:7], v[104:107]
	s_nop 2
	s_nop 0
	s_waitcnt lgkmcnt(0)
	s_barrier
	v_mfma_f32_16x16x32_bf16 v[6:9], v[248:251], v[4:7], v[8:11]
	s_nop 2
	v_mov_b32_e32 v10, v101
	v_mov_b32_e32 v4, v100
	s_nop 2
	v_mov_b32_e32 v11, v7
	v_mov_b32_e32 v5, v6
	v_pk_mul_f32 v[10:11], v[10:11], v[10:11]
	v_cvt_pk_bf16_f32 v6, v6, v7
	v_pk_fma_f32 v[4:5], v[4:5], v[4:5], v[10:11]
	v_mov_b32_e32 v10, v102
	v_mov_b32_e32 v11, v8
	v_pk_fma_f32 v[4:5], v[10:11], v[10:11], v[4:5]
	v_mov_b32_e32 v10, v103
	v_mov_b32_e32 v11, v9
	v_pk_fma_f32 v[4:5], v[10:11], v[10:11], v[4:5]
	v_cvt_pk_bf16_f32 v7, v8, v9
	v_add_f32_e32 v4, v4, v5
	ds_bpermute_b32 v5, v163, v4
	v_mov_b32_e32 v8, v204
	v_add_u32_e32 v11, 16, v207
	s_waitcnt lgkmcnt(0)
	v_add_f32_e32 v4, v4, v5
	ds_bpermute_b32 v5, v168, v4
	s_waitcnt lgkmcnt(0)
	v_add_f32_e32 v10, v4, v5
	v_cvt_pk_bf16_f32 v4, v100, v101
	v_cvt_pk_bf16_f32 v5, v102, v103
	ds_read_b128 v[100:103], v169 offset:34816
	ds_read_b128 v[104:107], v170 offset:53248
	s_waitcnt lgkmcnt(0)
	v_mfma_f32_16x16x32_bf16 v[84:87], v[104:107], v[100:103], v[84:87]
	ds_read_b128 v[104:107], v171 offset:53248
	s_waitcnt lgkmcnt(0)
	v_mfma_f32_16x16x32_bf16 v[96:99], v[104:107], v[100:103], v[96:99]
	ds_read_b128 v[100:103], v172 offset:34816
	ds_read_b128 v[104:107], v173 offset:53248
	s_waitcnt lgkmcnt(0)
	v_mfma_f32_16x16x32_bf16 v[84:87], v[104:107], v[100:103], v[84:87]
	ds_read_b128 v[104:107], v174 offset:53248
	s_waitcnt lgkmcnt(0)
	v_mfma_f32_16x16x32_bf16 v[96:99], v[104:107], v[100:103], v[96:99]
	s_nop 4
	v_mul_f32_e32 v84, v84, v8
	v_mul_f32_e32 v85, v85, v8
	v_mul_f32_e32 v86, v86, v8
	v_mul_f32_e32 v87, v87, v8
	s_nop 0
	v_cvt_pk_bf16_f32 v8, v84, s0
	ds_write_b16 v178, v8 offset:57856
	v_cvt_pk_bf16_f32 v8, v85, s0
	ds_write_b16 v178, v8 offset:58128
	v_cvt_pk_bf16_f32 v8, v86, s0
	ds_write_b16 v178, v8 offset:58400
	v_cvt_pk_bf16_f32 v8, v87, s0
	ds_write_b16 v178, v8 offset:58672
	s_nop 0
	v_mul_f32_e32 v96, v96, v204
	v_mul_f32_e32 v97, v97, v204
	v_mul_f32_e32 v98, v98, v204
	v_mul_f32_e32 v99, v99, v204
	s_nop 0
	v_cvt_pk_bf16_f32 v8, v96, s0
	ds_write_b16 v178, v8 offset:62208
	v_cvt_pk_bf16_f32 v8, v97, s0
	ds_write_b16 v178, v8 offset:62480
	v_cvt_pk_bf16_f32 v8, v98, s0
	ds_write_b16 v178, v8 offset:62752
	v_cvt_pk_bf16_f32 v8, v99, s0
	ds_write_b16 v178, v8 offset:63024
	ds_read_b128 v[100:103], v180 offset:34816
	ds_read_b128 v[104:107], v170 offset:53248
	s_waitcnt lgkmcnt(0)
	v_mfma_f32_16x16x32_bf16 v[88:91], v[104:107], v[100:103], v[88:91]
	ds_read_b128 v[104:107], v171 offset:53248
	v_mov_b32_e32 v8, v179
	s_waitcnt lgkmcnt(0)
	v_mfma_f32_16x16x32_bf16 v[92:95], v[104:107], v[100:103], v[92:95]
	ds_read_b128 v[100:103], v181 offset:34816
	ds_read_b128 v[104:107], v173 offset:53248
	s_waitcnt lgkmcnt(0)
	v_mfma_f32_16x16x32_bf16 v[88:91], v[104:107], v[100:103], v[88:91]
	ds_read_b128 v[104:107], v174 offset:53248
	s_waitcnt lgkmcnt(0)
	v_mfma_f32_16x16x32_bf16 v[92:95], v[104:107], v[100:103], v[92:95]
	s_nop 4
	v_mul_f32_e32 v88, v88, v8
	v_mul_f32_e32 v89, v89, v8
	v_mul_f32_e32 v90, v90, v8
	v_mul_f32_e32 v91, v91, v8
	s_nop 0
	v_cvt_pk_bf16_f32 v8, v88, s0
	ds_write_b16 v178, v8 offset:57888
	v_cvt_pk_bf16_f32 v8, v89, s0
	ds_write_b16 v178, v8 offset:58160
	v_cvt_pk_bf16_f32 v8, v90, s0
	ds_write_b16 v178, v8 offset:58432
	v_cvt_pk_bf16_f32 v8, v91, s0
	ds_write_b16 v178, v8 offset:58704
	s_nop 0
	v_mul_f32_e32 v92, v92, v179
	v_mul_f32_e32 v93, v93, v179
	v_mul_f32_e32 v94, v94, v179
	v_mul_f32_e32 v95, v95, v179
	s_nop 0
	v_cvt_pk_bf16_f32 v8, v92, s0
	ds_write_b16 v178, v8 offset:62240
	v_cvt_pk_bf16_f32 v8, v93, s0
	ds_write_b16 v178, v8 offset:62512
	v_cvt_pk_bf16_f32 v8, v94, s0
	ds_write_b16 v178, v8 offset:62784
	v_cvt_pk_bf16_f32 v8, v95, s0
	ds_write_b16 v178, v8 offset:63056
	s_waitcnt lgkmcnt(0)
	s_barrier
	s_branch .LBB0_1664
